# code placement: scan / mLSTM-out / OUT loop heads moved from 4 to 0 mod 8 bytes (two 4-byte pads)
# speedup vs baseline: 1.0155x; 1.0155x over previous
; #define LAS __attribute__((address_space(3)))
; #define GAS __attribute__((address_space(1)))
; __device__ __forceinline__ void mlstm_out_loop(unsigned char* ws, h16* Y, const float* ghead  , int u  , const int o_mout, const int o_end, const int ntc, const bool ctx_out, ...
;     const int lane = tid & 63, wid = __builtin_amdgcn_readfirstlane(tid >> 6), r32 = lane & 31, hi = lane >> 5, dir = wid >> 2, wl = wid & 3;
;     int b, h, tc; { const int a = u - o_mout, tci = a % ntc, bh = a / ntc; b = bh >> 2; h = bh & 3; tc = ctx_out ? tci : tci + 2; }
;     MoutPre R; mout_load(R, ws, b, h, tc, tid); bool have_mn = false;
;     { LAS float* GH = (LAS float*)(lds + MO_GH); if (tid < 256) GH[tid] = *(const GAS float*)(ghead + tid); }
;     unsigned tk = 0u; if (tid == 0) tk = __hip_atomic_fetch_add(head, 1u, RLX_AGENT);
;     for (;;) {
;         const unsigned nxt = tk; if (tid == 0) tk = __hip_atomic_fetch_add(head, 1u, RLX_AGENT);
;         const size_t rb = mout_rb(b, tc);
;         const int ci = tc < 2 ? (dir ? 1 - tc : tc) : 2 + (dir ? 15 - (tc - 2) : tc - 2);
;         const unsigned char* st = state_ptr(ws, b, h, dir, ci);
;         if (*acq == 0u) {
;             __syncthreads();
;             if (wid == 0) { unsigned sp = 0; for (;;) { const unsigned f0 = __hip_atomic_load(chain + 64 * lane, RLX_AGENT), f1 = __hip_atomic_load(chain + 64 * (lane + 64), RLX_AGENT);
.LBB0_227:
	v_readlane_b32 s62, v253, 5
	s_movk_i32 s87, 0x100
	v_readlane_b32 s63, v253, 6
	v_readlane_b32 s85, v253, 3
	v_readlane_b32 s96, v253, 7
	s_mov_b64 s[20:21], s[58:59]
	v_mov_b32_e32 v240, 1
	v_mov_b32_e32 v243, 0xff800000
	s_nop 0

;     __host__ __device__ bool next(int i, Unit& u) const { if (i != 0 || S.c >= 2 * (S.nwg - base)) return false; S.unit_of(base + (S.c >> 1), u); u.hm = S.c & 1; return true; }
; #define PG8_STAGE(bufoff, gbase) do { _Pragma("unroll") for (int _i = 0; _i < 2; ++_i) \
;         __builtin_amdgcn_global_load_lds((const unsigned*)((const char*)(gbase) + voffA[_i]), (LAS unsigned*)(lds + (bufoff) + ldsw + _i * 8192), 16, 0, 0); } while (0)
; #define PG8_WAIT_V(n) asm volatile("s_waitcnt vmcnt(" #n ")" ::: "memory")
; #define PG8_BAR __builtin_amdgcn_s_barrier()
; template <class Epi, bool ALIGN_EPI, bool SP2, bool BF = false, bool HALFM = false, class Order = StaticOrder>
; __device__ __forceinline__ void gemm_phase(LAS unsigned char* lds, const int tid, const Gemm g, const Order& S, const Epi& E, const bool dry = false) {
;     ...
;     for (int i = 0; i < 2; ++i) { int R, C; stage_rc(tid * 16 + i * 8192, R, C); voffA[i] = (unsigned)(R * K + C) * 2u; }
;     const size_t kstep = (size_t)(BK * 2);
;     const size_t hstep = (size_t)HALF * K * 2;
;     const size_t tstep = 2 * hstep;
;     const unsigned ldsw = (unsigned)wid * 1024u;
;     const int aoff = lds_byte(wr * 64 + fr, fq * 8), boff = lds_byte(wc * 32 + fr, fq * 8);
;     ...
;     Unit cur, nxt; int ui = 0;
;     if (!S.next(0, cur)) return;
;     f32x4 acc[2][2][4][2];
; #pragma unroll
;     for (int a = 0; a < 2; ++a)
; #pragma unroll
;         for (int b = 0; b < 2; ++b)
; #pragma unroll
;             for (int m = 0; m < 4; ++m)
; #pragma unroll
;                 for (int n = 0; n < 2; ++n) acc[a][b][m][n] = (f32x4){0.f, 0.f, 0.f, 0.f};
;     h16x8 At[4][2], B0[2][2], B1[2][2];
;     const char* cA = (const char*)g.A + (size_t)cur.pm * tstep + (HALFM ? (size_t)cur.hm * hstep : (size_t)0); const char* cB = (const char*)g.Bt + (size_t)cur.pn * tstep;
;     if constexpr (SP2) {
;         PG8_STAGE(PG8_SB(0, 0), cB); PG8_STAGE(PG8_SB(0, 1), cB + hstep); PG8_STAGE(PG8_SA(0, 0), cA); PG8_STAGE(PG8_SA(0, 1), cA + hstep);
;         if (wr == 1) PG8_BAR;
;         PG8_WAIT_V(2); PG8_BAR;
;         PG8_STAGE(PG8_SB(1, 0), cB + kstep); PG8_STAGE(PG8_SA(1, 0), cA + kstep); PG8_STAGE(PG8_SB(1, 1), cB + hstep + kstep);
;         PG8_WAIT_V(6); PG8_BAR;
.LBB0_555:
	s_lshl_b32 s12, s66, 4
	s_mul_i32 s3, s66, 0x3b800
	s_lshl_b32 s0, s66, 6
	s_ashr_i32 s13, s12, 31
	v_readlane_b32 s56, v252, 28
	s_ashr_i32 s1, s0, 31
	s_lshl_b64 s[12:13], s[12:13], 2
	v_readlane_b32 s64, v252, 36
	v_bfe_u32 v197, v246, 4, 2
	v_readlane_b32 s65, v252, 37
	s_add_u32 s12, s64, s12
	v_and_b32_e32 v196, 15, v246
	v_lshlrev_b32_e32 v16, 4, v197
	v_lshlrev_b32_e32 v17, 2, v246
	s_addc_u32 s13, s65, s13
	s_and_b32 s76, s10, 3
	v_lshl_or_b32 v16, v196, 6, v16
	s_lshl_b32 s5, s11, 13
	v_and_b32_e32 v17, 32, v17
	s_add_i32 s79, s74, 0x18000
	v_bitop3_b32 v18, v16, s5, v17 bitop3:0xde
	s_lshl_b32 s5, s76, 12
	s_add_i32 s80, s79, s9
	s_lshl_b32 s77, s11, 6
	v_bitop3_b32 v198, s5, v16, v17 bitop3:0xf6
	s_add_i32 s5, s74, 0x20400
	v_lshl_add_u64 v[8:9], v[8:9], 0, s[94:95]
	s_mov_b32 m0, s80
	s_add_i32 s81, s80, 0x2000
	s_add_i32 s82, s52, 0x8000
	s_add_i32 s83, s52, 0xa000
	s_waitcnt vmcnt(2)
	s_barrier
	global_load_lds_dwordx4 v[8:9], off
	v_lshl_add_u64 v[6:7], v[6:7], 0, s[94:95]
	s_mov_b32 m0, s81
	s_add_u32 s10, s36, 0x40080
	global_load_lds_dwordx4 v[6:7], off
	v_lshl_add_u64 v[2:3], v[2:3], 0, s[94:95]
	s_mov_b32 m0, s82
	s_addc_u32 s11, s37, 0
	s_add_i32 s84, s74, 0x1c000
	global_load_lds_dwordx4 v[2:3], off
	v_lshl_add_u64 v[2:3], v[4:5], 0, s[94:95]
	s_mov_b32 m0, s83
	s_add_i32 s85, s84, s9
	global_load_lds_dwordx4 v[2:3], off
	v_lshl_add_u64 v[2:3], s[10:11], 0, v[0:1]
	s_mov_b32 m0, s85
	s_add_i32 s86, s85, 0x2000
	global_load_lds_dwordx4 v[2:3], off
	v_lshl_add_u64 v[2:3], s[10:11], 0, v[164:165]
	s_mov_b32 m0, s86
	v_writelane_b32 v253, s12, 5
	global_load_lds_dwordx4 v[2:3], off
	v_lshlrev_b32_e32 v2, 14, v13
	v_and_b32_e32 v2, 0xffff8000, v2
	v_writelane_b32 v253, s13, 6
	v_lshl_add_u32 v2, v14, 11, v2
	v_and_b32_e32 v3, 1, v13
	v_writelane_b32 v253, s5, 7
	v_lshl_or_b32 v2, v3, 6, v2
	s_cmpk_lt_u32 s8, 0x100
	v_readlane_b32 s8, v253, 0
	v_lshl_add_u32 v166, v15, 1, v2
	v_lshlrev_b32_e32 v2, 14, v10
	s_cselect_b64 s[12:13], -1, 0
	s_lshl_b32 s5, s76, 7
	s_ashr_i32 s87, s73, 31
	v_readlane_b32 s9, v253, 1
	v_and_b32_e32 v2, 0xffff8000, v2
	v_readlane_b32 s70, v252, 42
	v_readlane_b32 s71, v252, 43
	s_waitcnt vmcnt(6)
	s_cmp_eq_u64 s[8:9], 0
	v_lshl_add_u32 v2, v11, 11, v2
	v_and_b32_e32 v3, 1, v10
	s_cselect_b64 s[14:15], -1, 0
	s_or_b32 s96, s3, s5
	s_add_i32 s3, s74, 0x21400
	v_lshl_or_b32 v2, v3, 6, v2
	v_readlane_b32 s70, v252, 58
	s_add_i32 s96, s96, 0x2680000
	v_writelane_b32 v253, s3, 8
	v_mov_b32_e32 v167, v1
	v_lshl_add_u32 v168, v12, 1, v2
	v_mov_b32_e32 v169, v1
	s_mov_b32 s10, 0
	v_add_u32_e32 v199, s74, v18
	s_lshl_b64 s[16:17], s[0:1], 2
	v_readlane_b32 s71, v252, 59
	v_readlane_b32 s57, v252, 29
	v_readlane_b32 s58, v252, 30
	v_readlane_b32 s59, v252, 31
	v_readlane_b32 s60, v252, 32
	v_readlane_b32 s61, v252, 33
	v_readlane_b32 s62, v252, 34
	v_readlane_b32 s63, v252, 35
	v_readlane_b32 s66, v252, 38
	v_readlane_b32 s67, v252, 39
	v_readlane_b32 s68, v252, 40
	v_readlane_b32 s69, v252, 41
	s_barrier
	s_mov_b32 s100, 0
	s_branch .LBB0_558
	s_nop 0
